# attention loop: every lgkmcnt(0) inside the K/V loop replaced by counted waits at first consumer (plus K swizzle row&15)
# speedup vs baseline: 1.0306x; 1.0306x over previous
; __device__ __forceinline__ void finishSM(f32x16& p0, f32x16& p1, float alpha, float& l_reg, bf16x8& pa0, bf16x8& pa1, bf16x8& pa2, bf16x8& pa3) {
;   for (int r = 0; r < 16; ++r) p1[r] = __builtin_amdgcn_exp2f(p1[r]);
;   float ps = 0; for (int r = 0; r < 16; ++r) ps += p0[r]; for (int r = 0; r < 16; ++r) ps += p1[r];
;   asm volatile("" : "+v"(ps));
;   l_reg = l_reg * alpha + ps;
;     ...
;   PK4(p0, 0, pa0); PK4(p0, 8, pa1); PK4(p1, 0, pa2); PK4(p1, 8, pa3);
;     ...
; }
; __device__ __forceinline__ void qkt(f32x16& p0, f32x16& p1, const bf16* Ks, const bf16x8* qr, int r32, int hi) {
;   p0 = f32x16{}; p1 = f32x16{};
;   for (int d0 = 0; d0 < 8; ++d0) { int cb = (d0 * 16 + hi * 8) * 2;
;     bf16x8 b0 = *reinterpret_cast<const bf16x8*>((const char*)Ks + KSWZ(r32, cb));
;     bf16x8 b1 = *reinterpret_cast<const bf16x8*>((const char*)Ks + KSWZ(32 + r32, cb));
;     p0 = __builtin_amdgcn_mfma_f32_32x32x16_bf16(b0, qr[d0], p0, 0, 0, 0);
;     p1 = __builtin_amdgcn_mfma_f32_32x32x16_bf16(b1, qr[d0], p1, 0, 0, 0); }
; }
; __device__ __forceinline__ int v_st(int k, int c) { const int kk = k;
;   return ((kk >> 3) * 4 + (c >> 5)) * 512 + ((kk & 7) * 32 + (c & 31)) * 2; }
; __device__ __forceinline__ int v_rd_base(int lane) { return ((lane & 3) << 3) | (((lane >> 2) & 3) << 6) | (((lane >> 4) & 1) << 5) | (((lane >> 5) & 1) << 8); }
; template <int OFF> __device__ __forceinline__ s16x4 tr_read(int vb) {
;   s16x4 r; asm volatile("ds_read_b64_tr_b16 %0, %1 offset:%2" : "=&v"(r) : "v"(vb), "i"(OFF) : "memory"); return r;
; }
; template <int D0> __device__ __forceinline__ void pv_one(f32x16& od, int vb, bf16x8 pa0, bf16x8 pa1, bf16x8 pa2, bf16x8 pa3) {
;   const s16x4 l0 = tr_read<v_rd_off(D0, 0, 0)>(vb), h0 = tr_read<v_rd_off(D0, 0, 1)>(vb), l1 = tr_read<v_rd_off(D0, 1, 0)>(vb), h1 = tr_read<v_rd_off(D0, 1, 1)>(vb);
;   const s16x4 l2 = tr_read<v_rd_off(D0, 2, 0)>(vb), h2 = tr_read<v_rd_off(D0, 2, 1)>(vb), l3 = tr_read<v_rd_off(D0, 3, 0)>(vb), h3 = tr_read<v_rd_off(D0, 3, 1)>(vb);
;   asm volatile("s_waitcnt lgkmcnt(0)" ::: "memory"); SBAR();
;     ...
;   od = __builtin_amdgcn_mfma_f32_32x32x16_bf16(pa0, PK(l0, h0), od, 0, 0, 0);
;   od = __builtin_amdgcn_mfma_f32_32x32x16_bf16(pa1, PK(l1, h1), od, 0, 0, 0);
;   od = __builtin_amdgcn_mfma_f32_32x32x16_bf16(pa2, PK(l2, h2), od, 0, 0, 0);
;   od = __builtin_amdgcn_mfma_f32_32x32x16_bf16(pa3, PK(l3, h3), od, 0, 0, 0);
;     ...
; }
.LBB0_461:
	s_mov_b32 s40, s33
	s_addk_i32 s33, 0xc000
	s_and_b32 s42, s33, 0xc000
	s_add_i32 s33, s57, s42
	v_add_u32_e32 v84, s33, v178
	ds_read_b128 v[80:83], v84
	ds_read_b128 v[84:87], v84 offset:8192
	v_add_u32_e32 v202, s33, v179
	ds_read_b128 v[198:201], v202
	ds_read_b128 v[202:205], v202 offset:8192
	v_add_u32_e32 v206, s33, v181
	s_waitcnt lgkmcnt(3)
	v_mfma_f32_32x32x16_bf16 v[96:111], v[80:83], v[136:139], 0
	v_add_u32_e32 v214, s33, v182
	v_exp_f32_e32 v238, v64
	v_add_f32_e32 v64, 0, v196
	v_add_f32_e32 v64, v197, v64
	v_add_u32_e32 v222, s33, v183
	v_add_f32_e32 v64, v193, v64
	v_add_f32_e32 v64, v195, v64
	s_waitcnt lgkmcnt(2)
	v_mfma_f32_32x32x16_bf16 v[80:95], v[84:87], v[136:139], 0
	v_add_f32_e32 v64, v191, v64
	v_add_f32_e32 v64, v194, v64
	v_add_f32_e32 v64, v190, v64
	v_add_f32_e32 v64, v192, v64
	v_add_f32_e32 v64, v169, v64
	v_add_f32_e32 v64, v171, v64
	v_add_u32_e32 v226, s33, v184
	s_waitcnt lgkmcnt(1)
	v_mfma_f32_32x32x16_bf16 v[96:111], v[198:201], v[140:143], v[96:111]
	v_add_f32_e32 v64, v167, v64
	v_add_f32_e32 v64, v170, v64
	v_add_f32_e32 v64, v165, v64
	v_add_f32_e32 v64, v168, v64
	v_add_f32_e32 v64, v164, v64
	v_add_f32_e32 v64, v166, v64
	v_exp_f32_e32 v239, v68
	s_waitcnt lgkmcnt(0)
	v_mfma_f32_32x32x16_bf16 v[80:95], v[202:205], v[140:143], v[80:95]
	v_add_u32_e32 v202, s33, v180
	ds_read_b128 v[198:201], v202
	ds_read_b128 v[202:205], v202 offset:8192
	v_add_f32_e32 v64, v238, v64
	v_exp_f32_e32 v240, v69
	v_add_u32_e32 v234, s33, v185
	v_exp_f32_e32 v241, v70
	v_exp_f32_e32 v242, v71
	s_waitcnt lgkmcnt(1)
	v_mfma_f32_32x32x16_bf16 v[96:111], v[198:201], v[132:135], v[96:111]
	ds_read_b128 v[198:201], v206
	ds_read_b128 v[206:209], v206 offset:8192
	ds_read_b128 v[210:213], v214
	ds_read_b128 v[214:217], v214 offset:8192
	ds_read_b128 v[218:221], v222
	ds_read_b128 v[222:225], v222 offset:8192
	v_exp_f32_e32 v243, v76
	v_exp_f32_e32 v244, v77
	v_exp_f32_e32 v245, v78
	v_exp_f32_e32 v79, v79
	s_waitcnt lgkmcnt(6)
	v_mfma_f32_32x32x16_bf16 v[80:95], v[202:205], v[132:135], v[80:95]
	ds_read_b128 v[202:205], v226
	ds_read_b128 v[226:229], v226 offset:8192
	ds_read_b128 v[230:233], v234
	ds_read_b128 v[234:237], v234 offset:8192
	s_waitcnt lgkmcnt(9)
	v_mfma_f32_32x32x16_bf16 v[96:111], v[198:201], v[128:131], v[96:111]
	v_exp_f32_e32 v199, v65
	v_exp_f32_e32 v200, v66
	v_exp_f32_e32 v201, v67
	v_add_f32_e32 v64, v199, v64
	v_add_f32_e32 v64, v200, v64
	v_add_f32_e32 v64, v201, v64
	s_waitcnt lgkmcnt(8)
	v_mfma_f32_32x32x16_bf16 v[80:95], v[206:209], v[128:131], v[80:95]
	v_exp_f32_e32 v206, v72
	v_add_f32_e32 v64, v239, v64
	v_exp_f32_e32 v207, v73
	v_add_f32_e32 v64, v240, v64
	v_exp_f32_e32 v208, v74
	v_add_f32_e32 v64, v241, v64
	v_exp_f32_e32 v209, v75
	s_waitcnt lgkmcnt(7)
	v_mfma_f32_32x32x16_bf16 v[96:111], v[210:213], v[124:127], v[96:111]
	v_add_f32_e32 v64, v242, v64
	v_add_f32_e32 v64, v206, v64
	v_add_f32_e32 v64, v207, v64
	v_add_f32_e32 v64, v208, v64
	v_add_f32_e32 v64, v209, v64
	v_add_f32_e32 v64, v243, v64
	v_add_f32_e32 v64, v244, v64
	s_waitcnt lgkmcnt(6)
	v_mfma_f32_32x32x16_bf16 v[80:95], v[214:217], v[124:127], v[80:95]
	v_add_f32_e32 v64, v245, v64
	v_add_f32_e32 v198, v79, v64
	v_cvt_pk_bf16_f32 v64, v196, v197
	v_cvt_pk_bf16_f32 v65, v193, v195
	v_cvt_pk_bf16_f32 v66, v191, v194
	v_cvt_pk_bf16_f32 v67, v190, v192
	s_waitcnt lgkmcnt(5)
	v_mfma_f32_32x32x16_bf16 v[96:111], v[218:221], v[120:123], v[96:111]
	v_cvt_pk_bf16_f32 v68, v169, v171
	v_cvt_pk_bf16_f32 v69, v167, v170
	v_cvt_pk_bf16_f32 v70, v165, v168
	v_cvt_pk_bf16_f32 v71, v164, v166
	v_cvt_pk_bf16_f32 v72, v238, v199
	v_cvt_pk_bf16_f32 v73, v200, v201
	v_cvt_pk_bf16_f32 v74, v239, v240
	s_waitcnt lgkmcnt(4)
	v_mfma_f32_32x32x16_bf16 v[80:95], v[222:225], v[120:123], v[80:95]
	v_cvt_pk_bf16_f32 v75, v241, v242
	v_cvt_pk_bf16_f32 v76, v206, v207
	v_cvt_pk_bf16_f32 v77, v208, v209
	v_cvt_pk_bf16_f32 v78, v243, v244
	v_cvt_pk_bf16_f32 v79, v245, v79
	s_waitcnt lgkmcnt(3)
	v_mfma_f32_32x32x16_bf16 v[96:111], v[202:205], v[116:119], v[96:111]
	s_waitcnt lgkmcnt(2)
	v_mfma_f32_32x32x16_bf16 v[80:95], v[226:229], v[116:119], v[80:95]
	s_waitcnt lgkmcnt(1)
	v_mfma_f32_32x32x16_bf16 v[96:111], v[230:233], v[112:115], v[96:111]
	s_waitcnt lgkmcnt(0)
	v_mfma_f32_32x32x16_bf16 v[80:95], v[234:237], v[112:115], v[80:95]
	s_add_i32 s33, s40, 0x4000
	s_and_b32 s33, s33, 0xc000
	v_lshl_add_u64 v[164:165], s[38:39], 0, v[156:157]
	s_add_i32 s41, s67, s33
	v_lshl_add_u64 v[166:167], v[164:165], 0, s[22:23]
	s_mov_b32 m0, s41
	s_add_i32 s33, s72, s33
	global_load_lds_dwordx4 v[166:167], off
	v_lshl_add_u64 v[166:167], s[38:39], 0, v[158:159]
	v_lshl_add_u64 v[168:169], v[166:167], 0, s[22:23]
	s_add_i32 m0, s41, 0x2000
	s_nop 0
	global_load_lds_dwordx4 v[168:169], off
	v_lshl_add_u64 v[168:169], s[38:39], 0, v[162:163]
	v_lshl_add_u64 v[170:171], v[168:169], 0, s[24:25]
	s_mov_b32 m0, s33
	s_nop 0
	global_load_lds_dwordx4 v[170:171], off
	v_lshl_add_u64 v[170:171], s[38:39], 0, v[160:161]
	v_lshl_add_u64 v[190:191], v[170:171], 0, s[24:25]
	s_add_i32 m0, s33, 0x2000
	s_nop 0
	global_load_lds_dwordx4 v[190:191], off
	s_add_i32 s33, s40, 0x8000
	s_and_b32 s43, s33, 0xc000
	v_add_u32_e32 v199, s43, v176
	ds_read_b64_tr_b16 v[190:191], v199 offset:0
	ds_read_b64_tr_b16 v[192:193], v199 offset:0x800
	ds_read_b64_tr_b16 v[194:195], v199 offset:0x1000
	ds_read_b64_tr_b16 v[196:197], v199 offset:0x1800
	ds_read_b64_tr_b16 v[200:201], v199 offset:0x2000
	ds_read_b64_tr_b16 v[202:203], v199 offset:0x2800
	ds_read_b64_tr_b16 v[204:205], v199 offset:0x3000
	ds_read_b64_tr_b16 v[206:207], v199 offset:0x3800
	s_nop 0
	s_waitcnt lgkmcnt(6)
; __device__ __forceinline__ void finishSM(f32x16& p0, f32x16& p1, float alpha, float& l_reg, bf16x8& pa0, bf16x8& pa1, bf16x8& pa2, bf16x8& pa3) {
;   for (int r = 0; r < 16; ++r) p1[r] = __builtin_amdgcn_exp2f(p1[r]);
;   float ps = 0; for (int r = 0; r < 16; ++r) ps += p0[r]; for (int r = 0; r < 16; ++r) ps += p1[r];
;   asm volatile("" : "+v"(ps));
;   l_reg = l_reg * alpha + ps;
;     ...
;   PK4(p0, 0, pa0); PK4(p0, 8, pa1); PK4(p1, 0, pa2); PK4(p1, 8, pa3);
;     ...
; }
; __device__ __forceinline__ void qkt(f32x16& p0, f32x16& p1, const bf16* Ks, const bf16x8* qr, int r32, int hi) {
;   p0 = f32x16{}; p1 = f32x16{};
;   for (int d0 = 0; d0 < 8; ++d0) { int cb = (d0 * 16 + hi * 8) * 2;
;     bf16x8 b0 = *reinterpret_cast<const bf16x8*>((const char*)Ks + KSWZ(r32, cb));
;     bf16x8 b1 = *reinterpret_cast<const bf16x8*>((const char*)Ks + KSWZ(32 + r32, cb));
;     p0 = __builtin_amdgcn_mfma_f32_32x32x16_bf16(b0, qr[d0], p0, 0, 0, 0);
;     p1 = __builtin_amdgcn_mfma_f32_32x32x16_bf16(b1, qr[d0], p1, 0, 0, 0); }
; }
; __device__ __forceinline__ int v_st(int k, int c) { const int kk = k;
;   return ((kk >> 3) * 4 + (c >> 5)) * 512 + ((kk & 7) * 32 + (c & 31)) * 2; }
; __device__ __forceinline__ int v_rd_base(int lane) { return ((lane & 3) << 3) | (((lane >> 2) & 3) << 6) | (((lane >> 4) & 1) << 5) | (((lane >> 5) & 1) << 8); }
; template <int OFF> __device__ __forceinline__ s16x4 tr_read(int vb) {
;   s16x4 r; asm volatile("ds_read_b64_tr_b16 %0, %1 offset:%2" : "=&v"(r) : "v"(vb), "i"(OFF) : "memory"); return r;
; }
; template <int D0> __device__ __forceinline__ void pv_one(f32x16& od, int vb, bf16x8 pa0, bf16x8 pa1, bf16x8 pa2, bf16x8 pa3) {
;   const s16x4 l0 = tr_read<v_rd_off(D0, 0, 0)>(vb), h0 = tr_read<v_rd_off(D0, 0, 1)>(vb), l1 = tr_read<v_rd_off(D0, 1, 0)>(vb), h1 = tr_read<v_rd_off(D0, 1, 1)>(vb);
;   const s16x4 l2 = tr_read<v_rd_off(D0, 2, 0)>(vb), h2 = tr_read<v_rd_off(D0, 2, 1)>(vb), l3 = tr_read<v_rd_off(D0, 3, 0)>(vb), h3 = tr_read<v_rd_off(D0, 3, 1)>(vb);
;   asm volatile("s_waitcnt lgkmcnt(0)" ::: "memory"); SBAR();
;     ...
;   od = __builtin_amdgcn_mfma_f32_32x32x16_bf16(pa0, PK(l0, h0), od, 0, 0, 0);
;   od = __builtin_amdgcn_mfma_f32_32x32x16_bf16(pa1, PK(l1, h1), od, 0, 0, 0);
;   od = __builtin_amdgcn_mfma_f32_32x32x16_bf16(pa2, PK(l2, h2), od, 0, 0, 0);
;   od = __builtin_amdgcn_mfma_f32_32x32x16_bf16(pa3, PK(l3, h3), od, 0, 0, 0);
;     ...
; }
	v_mfma_f32_32x32x16_bf16 v[48:63], v[64:67], v[190:193], v[48:63]
	ds_read_b64_tr_b16 v[190:191], v199 offset:0x200
	ds_read_b64_tr_b16 v[192:193], v199 offset:0xa00
	s_waitcnt lgkmcnt(6)
	v_mfma_f32_32x32x16_bf16 v[48:63], v[68:71], v[194:197], v[48:63]
	ds_read_b64_tr_b16 v[194:195], v199 offset:0x1200
	ds_read_b64_tr_b16 v[196:197], v199 offset:0x1a00
	s_waitcnt lgkmcnt(6)
	v_mfma_f32_32x32x16_bf16 v[48:63], v[72:75], v[200:203], v[48:63]
	ds_read_b64_tr_b16 v[200:201], v199 offset:0x2200
	ds_read_b64_tr_b16 v[202:203], v199 offset:0x2a00
	ds_read_b64_tr_b16 v[208:209], v199 offset:0x3200
	ds_read_b64_tr_b16 v[210:211], v199 offset:0x3a00
	s_waitcnt lgkmcnt(8)
	v_mfma_f32_32x32x16_bf16 v[48:63], v[76:79], v[204:207], v[48:63]
	s_waitcnt lgkmcnt(6)
	v_mfma_f32_32x32x16_bf16 v[32:47], v[64:67], v[190:193], v[32:47]
	ds_read_b64_tr_b16 v[190:191], v199 offset:0x400
	ds_read_b64_tr_b16 v[192:193], v199 offset:0xc00
	s_waitcnt lgkmcnt(6)
	v_mfma_f32_32x32x16_bf16 v[32:47], v[68:71], v[194:197], v[32:47]
	ds_read_b64_tr_b16 v[194:195], v199 offset:0x1400
	ds_read_b64_tr_b16 v[196:197], v199 offset:0x1c00
	s_waitcnt lgkmcnt(6)
	v_mfma_f32_32x32x16_bf16 v[32:47], v[72:75], v[200:203], v[32:47]
	ds_read_b64_tr_b16 v[200:201], v199 offset:0x2400
	ds_read_b64_tr_b16 v[202:203], v199 offset:0x2c00
	ds_read_b64_tr_b16 v[204:205], v199 offset:0x3400
	ds_read_b64_tr_b16 v[206:207], v199 offset:0x3c00
	s_waitcnt lgkmcnt(8)
	v_mfma_f32_32x32x16_bf16 v[32:47], v[76:79], v[208:211], v[32:47]
	s_waitcnt lgkmcnt(6)
	v_mfma_f32_32x32x16_bf16 v[16:31], v[64:67], v[190:193], v[16:31]
	ds_read_b64_tr_b16 v[190:191], v199 offset:0x600
	ds_read_b64_tr_b16 v[192:193], v199 offset:0xe00
	s_waitcnt lgkmcnt(6)
	v_mfma_f32_32x32x16_bf16 v[16:31], v[68:71], v[194:197], v[16:31]
	ds_read_b64_tr_b16 v[194:195], v199 offset:0x1600
	ds_read_b64_tr_b16 v[196:197], v199 offset:0x1e00
	s_waitcnt lgkmcnt(6)
	v_mfma_f32_32x32x16_bf16 v[16:31], v[72:75], v[200:203], v[16:31]
	ds_read_b64_tr_b16 v[200:201], v199 offset:0x2600
	ds_read_b64_tr_b16 v[202:203], v199 offset:0x2e00
	ds_read_b64_tr_b16 v[208:209], v199 offset:0x3600
	ds_read_b64_tr_b16 v[210:211], v199 offset:0x3e00
	s_waitcnt lgkmcnt(8)
	v_mfma_f32_32x32x16_bf16 v[16:31], v[76:79], v[204:207], v[16:31]
	s_waitcnt lgkmcnt(6)
	v_mfma_f32_32x32x16_bf16 v[0:15], v[64:67], v[190:193], v[0:15]
	s_waitcnt vmcnt(4)
	v_exp_f32_e32 v232, v96
	v_exp_f32_e32 v233, v97
	v_exp_f32_e32 v234, v98
	v_exp_f32_e32 v235, v99
	v_exp_f32_e32 v236, v100
	s_waitcnt lgkmcnt(4)
	v_mfma_f32_32x32x16_bf16 v[0:15], v[68:71], v[194:197], v[0:15]
	v_exp_f32_e32 v237, v101
	v_exp_f32_e32 v238, v102
	v_exp_f32_e32 v239, v103
	v_exp_f32_e32 v240, v104
	v_exp_f32_e32 v241, v105
	v_exp_f32_e32 v242, v106
	v_exp_f32_e32 v243, v107
	s_waitcnt lgkmcnt(2)
	v_mfma_f32_32x32x16_bf16 v[0:15], v[72:75], v[200:203], v[0:15]
	v_exp_f32_e32 v244, v108
	v_exp_f32_e32 v245, v109
	v_exp_f32_e32 v246, v110
	v_exp_f32_e32 v247, v111
	s_waitcnt lgkmcnt(0)
	s_barrier
	v_mfma_f32_32x32x16_bf16 v[0:15], v[76:79], v[208:211], v[0:15]
	s_and_b32 s40, s40, 0xc000
	s_add_i32 s40, s57, s40
	v_add_u32_e32 v68, s40, v178
	ds_read_b128 v[64:67], v68
	ds_read_b128 v[68:71], v68 offset:8192
	v_add_u32_e32 v194, s40, v179
	ds_read_b128 v[190:193], v194
	ds_read_b128 v[194:197], v194 offset:8192
	v_add_u32_e32 v199, s40, v181
	s_waitcnt lgkmcnt(3)
	v_mfma_f32_32x32x16_bf16 v[96:111], v[64:67], v[136:139], 0
	v_exp_f32_e32 v80, v80
	v_exp_f32_e32 v81, v81
	v_exp_f32_e32 v82, v82
	v_exp_f32_e32 v83, v83
	v_exp_f32_e32 v87, v87
	v_exp_f32_e32 v248, v93
	v_exp_f32_e32 v249, v94
	s_waitcnt lgkmcnt(2)
	v_mfma_f32_32x32x16_bf16 v[64:79], v[68:71], v[136:139], 0
	s_waitcnt lgkmcnt(1)
	v_mfma_f32_32x32x16_bf16 v[96:111], v[190:193], v[140:143], v[96:111]
	s_waitcnt lgkmcnt(0)
	v_mfma_f32_32x32x16_bf16 v[64:79], v[194:197], v[140:143], v[64:79]
	v_add_u32_e32 v194, s40, v180
	ds_read_b128 v[190:193], v194
	ds_read_b128 v[194:197], v194 offset:8192
	s_waitcnt lgkmcnt(1)
	v_mfma_f32_32x32x16_bf16 v[96:111], v[190:193], v[132:135], v[96:111]
	ds_read_b128 v[190:193], v199
	ds_read_b128 v[200:203], v199 offset:8192
	v_add_u32_e32 v199, s40, v182
	ds_read_b128 v[204:207], v199
	ds_read_b128 v[208:211], v199 offset:8192
	v_add_u32_e32 v199, s40, v183
	ds_read_b128 v[212:215], v199
	ds_read_b128 v[216:219], v199 offset:8192
	v_add_u32_e32 v199, s40, v184
	s_waitcnt lgkmcnt(6)
	v_mfma_f32_32x32x16_bf16 v[64:79], v[194:197], v[132:135], v[64:79]
	ds_read_b128 v[194:197], v199
	ds_read_b128 v[220:223], v199 offset:8192
	v_add_u32_e32 v199, s40, v185
	ds_read_b128 v[224:227], v199
	ds_read_b128 v[228:231], v199 offset:8192
	s_waitcnt lgkmcnt(9)
	v_mfma_f32_32x32x16_bf16 v[96:111], v[190:193], v[128:131], v[96:111]
	v_exp_f32_e32 v190, v84
	v_add_f32_e32 v84, 0, v232
	v_add_f32_e32 v84, v233, v84
	v_add_f32_e32 v84, v234, v84
	v_add_f32_e32 v84, v235, v84
	v_add_f32_e32 v84, v236, v84
	v_add_f32_e32 v84, v237, v84
	s_waitcnt lgkmcnt(8)
	v_mfma_f32_32x32x16_bf16 v[64:79], v[200:203], v[128:131], v[64:79]
	v_add_f32_e32 v84, v238, v84
	v_add_f32_e32 v84, v239, v84
	v_add_f32_e32 v84, v240, v84
	v_add_f32_e32 v84, v241, v84
	v_add_f32_e32 v84, v242, v84
	v_add_f32_e32 v84, v243, v84
	v_add_f32_e32 v84, v244, v84
	s_waitcnt lgkmcnt(7)
	v_mfma_f32_32x32x16_bf16 v[96:111], v[204:207], v[124:127], v[96:111]
	v_add_f32_e32 v84, v245, v84
	v_add_f32_e32 v84, v246, v84
	v_add_f32_e32 v84, v247, v84
	v_add_f32_e32 v84, v80, v84
	v_exp_f32_e32 v191, v85
	v_add_f32_e32 v84, v81, v84
	v_exp_f32_e32 v192, v86
	s_waitcnt lgkmcnt(6)
; __device__ __forceinline__ void finishSM(f32x16& p0, f32x16& p1, float alpha, float& l_reg, bf16x8& pa0, bf16x8& pa1, bf16x8& pa2, bf16x8& pa3) {
;   for (int r = 0; r < 16; ++r) p1[r] = __builtin_amdgcn_exp2f(p1[r]);
;   float ps = 0; for (int r = 0; r < 16; ++r) ps += p0[r]; for (int r = 0; r < 16; ++r) ps += p1[r];
;   asm volatile("" : "+v"(ps));
;   l_reg = l_reg * alpha + ps;
;     ...
;   PK4(p0, 0, pa0); PK4(p0, 8, pa1); PK4(p1, 0, pa2); PK4(p1, 8, pa3);
;     ...
; }
; __device__ __forceinline__ void qkt(f32x16& p0, f32x16& p1, const bf16* Ks, const bf16x8* qr, int r32, int hi) {
;   p0 = f32x16{}; p1 = f32x16{};
;   for (int d0 = 0; d0 < 8; ++d0) { int cb = (d0 * 16 + hi * 8) * 2;
;     bf16x8 b0 = *reinterpret_cast<const bf16x8*>((const char*)Ks + KSWZ(r32, cb));
;     bf16x8 b1 = *reinterpret_cast<const bf16x8*>((const char*)Ks + KSWZ(32 + r32, cb));
;     p0 = __builtin_amdgcn_mfma_f32_32x32x16_bf16(b0, qr[d0], p0, 0, 0, 0);
;     p1 = __builtin_amdgcn_mfma_f32_32x32x16_bf16(b1, qr[d0], p1, 0, 0, 0); }
; }
; __device__ __forceinline__ int v_st(int k, int c) { const int kk = k;
;   return ((kk >> 3) * 4 + (c >> 5)) * 512 + ((kk & 7) * 32 + (c & 31)) * 2; }
; __device__ __forceinline__ int v_rd_base(int lane) { return ((lane & 3) << 3) | (((lane >> 2) & 3) << 6) | (((lane >> 4) & 1) << 5) | (((lane >> 5) & 1) << 8); }
; template <int OFF> __device__ __forceinline__ s16x4 tr_read(int vb) {
;   s16x4 r; asm volatile("ds_read_b64_tr_b16 %0, %1 offset:%2" : "=&v"(r) : "v"(vb), "i"(OFF) : "memory"); return r;
; }
; template <int D0> __device__ __forceinline__ void pv_one(f32x16& od, int vb, bf16x8 pa0, bf16x8 pa1, bf16x8 pa2, bf16x8 pa3) {
;   const s16x4 l0 = tr_read<v_rd_off(D0, 0, 0)>(vb), h0 = tr_read<v_rd_off(D0, 0, 1)>(vb), l1 = tr_read<v_rd_off(D0, 1, 0)>(vb), h1 = tr_read<v_rd_off(D0, 1, 1)>(vb);
;   const s16x4 l2 = tr_read<v_rd_off(D0, 2, 0)>(vb), h2 = tr_read<v_rd_off(D0, 2, 1)>(vb), l3 = tr_read<v_rd_off(D0, 3, 0)>(vb), h3 = tr_read<v_rd_off(D0, 3, 1)>(vb);
;   asm volatile("s_waitcnt lgkmcnt(0)" ::: "memory"); SBAR();
;     ...
;   od = __builtin_amdgcn_mfma_f32_32x32x16_bf16(pa0, PK(l0, h0), od, 0, 0, 0);
;   od = __builtin_amdgcn_mfma_f32_32x32x16_bf16(pa1, PK(l1, h1), od, 0, 0, 0);
;   od = __builtin_amdgcn_mfma_f32_32x32x16_bf16(pa2, PK(l2, h2), od, 0, 0, 0);
;   od = __builtin_amdgcn_mfma_f32_32x32x16_bf16(pa3, PK(l3, h3), od, 0, 0, 0);
;     ...
; }
	v_mfma_f32_32x32x16_bf16 v[64:79], v[208:211], v[124:127], v[64:79]
	v_add_f32_e32 v84, v82, v84
	v_add_f32_e32 v84, v83, v84
	v_exp_f32_e32 v193, v88
	v_add_f32_e32 v84, v190, v84
	v_exp_f32_e32 v200, v89
	v_add_f32_e32 v84, v191, v84
	v_exp_f32_e32 v201, v90
	s_waitcnt lgkmcnt(5)
	v_mfma_f32_32x32x16_bf16 v[96:111], v[212:215], v[120:123], v[96:111]
	v_add_f32_e32 v84, v192, v84
	v_exp_f32_e32 v202, v91
	v_add_f32_e32 v84, v87, v84
	v_exp_f32_e32 v203, v92
	v_add_f32_e32 v84, v193, v84
	v_add_f32_e32 v84, v200, v84
	v_add_f32_e32 v84, v201, v84
	s_waitcnt lgkmcnt(4)
	v_mfma_f32_32x32x16_bf16 v[64:79], v[216:219], v[120:123], v[64:79]
	v_exp_f32_e32 v204, v95
	v_add_f32_e32 v84, v202, v84
	v_add_f32_e32 v84, v203, v84
	v_add_f32_e32 v84, v248, v84
	v_add_f32_e32 v84, v249, v84
	v_add_f32_e32 v199, v204, v84
	s_waitcnt lgkmcnt(3)
	v_mfma_f32_32x32x16_bf16 v[96:111], v[194:197], v[116:119], v[96:111]
	v_cvt_pk_bf16_f32 v92, v232, v233
	v_cvt_pk_bf16_f32 v93, v234, v235
	v_cvt_pk_bf16_f32 v94, v236, v237
	v_cvt_pk_bf16_f32 v95, v238, v239
	v_cvt_pk_bf16_f32 v88, v240, v241
	v_cvt_pk_bf16_f32 v89, v242, v243
	v_cvt_pk_bf16_f32 v90, v244, v245
	s_waitcnt lgkmcnt(2)
	v_mfma_f32_32x32x16_bf16 v[64:79], v[220:223], v[116:119], v[64:79]
	v_cvt_pk_bf16_f32 v91, v246, v247
	v_cvt_pk_bf16_f32 v84, v80, v81
	v_cvt_pk_bf16_f32 v85, v82, v83
	v_cvt_pk_bf16_f32 v86, v190, v191
	v_cvt_pk_bf16_f32 v87, v192, v87
	v_cvt_pk_bf16_f32 v80, v193, v200
	v_cvt_pk_bf16_f32 v81, v201, v202
	s_waitcnt lgkmcnt(1)
	v_mfma_f32_32x32x16_bf16 v[96:111], v[224:227], v[112:115], v[96:111]
	v_cvt_pk_bf16_f32 v82, v203, v248
	v_cvt_pk_bf16_f32 v83, v249, v204
	s_waitcnt lgkmcnt(0)
	v_mfma_f32_32x32x16_bf16 v[64:79], v[228:231], v[112:115], v[64:79]
	s_cmp_ge_u32 s73, s37
	s_cselect_b64 s[40:41], -1, 0
	s_and_b64 vcc, exec, s[40:41]
	s_cbranch_vccnz .LBB0_463
	s_add_i32 s74, s67, s43
	v_lshl_add_u64 v[164:165], v[164:165], 0, s[26:27]
	s_mov_b32 m0, s74
	s_add_i32 s43, s72, s43
	global_load_lds_dwordx4 v[164:165], off
	v_lshl_add_u64 v[164:165], v[166:167], 0, s[26:27]
	s_add_i32 m0, s74, 0x2000
	s_nop 0
	global_load_lds_dwordx4 v[164:165], off
	v_lshl_add_u64 v[164:165], v[168:169], 0, s[28:29]
	s_mov_b32 m0, s43
	s_nop 0
	global_load_lds_dwordx4 v[164:165], off
	v_lshl_add_u64 v[164:165], v[170:171], 0, s[28:29]
	s_add_i32 m0, s43, 0x2000
	s_nop 0
	global_load_lds_dwordx4 v[164:165], off
.LBB0_463:
	v_add_u32_e32 v204, s42, v176
	ds_read_b64_tr_b16 v[164:165], v204 offset:0
	ds_read_b64_tr_b16 v[166:167], v204 offset:0x800
	ds_read_b64_tr_b16 v[168:169], v204 offset:0x1000
	ds_read_b64_tr_b16 v[170:171], v204 offset:0x1800
	ds_read_b64_tr_b16 v[190:191], v204 offset:0x2000
	ds_read_b64_tr_b16 v[192:193], v204 offset:0x2800
	ds_read_b64_tr_b16 v[194:195], v204 offset:0x3000
	ds_read_b64_tr_b16 v[196:197], v204 offset:0x3800
	s_nop 0
	s_waitcnt lgkmcnt(6)
	v_mfma_f32_32x32x16_bf16 v[48:63], v[92:95], v[164:167], v[48:63]
	ds_read_b64_tr_b16 v[164:165], v204 offset:0x200
	ds_read_b64_tr_b16 v[166:167], v204 offset:0xa00
	s_waitcnt lgkmcnt(6)
	v_mfma_f32_32x32x16_bf16 v[48:63], v[88:91], v[168:171], v[48:63]
	ds_read_b64_tr_b16 v[168:169], v204 offset:0x1200
	ds_read_b64_tr_b16 v[170:171], v204 offset:0x1a00
	s_waitcnt lgkmcnt(6)
	v_mfma_f32_32x32x16_bf16 v[48:63], v[84:87], v[190:193], v[48:63]
	ds_read_b64_tr_b16 v[190:191], v204 offset:0x2200
	ds_read_b64_tr_b16 v[192:193], v204 offset:0x2a00
	ds_read_b64_tr_b16 v[200:201], v204 offset:0x3200
	ds_read_b64_tr_b16 v[202:203], v204 offset:0x3a00
	s_waitcnt lgkmcnt(8)
	v_mfma_f32_32x32x16_bf16 v[48:63], v[80:83], v[194:197], v[48:63]
	s_waitcnt lgkmcnt(6)
	v_mfma_f32_32x32x16_bf16 v[32:47], v[92:95], v[164:167], v[32:47]
	ds_read_b64_tr_b16 v[164:165], v204 offset:0x400
	ds_read_b64_tr_b16 v[166:167], v204 offset:0xc00
	s_waitcnt lgkmcnt(6)
	v_mfma_f32_32x32x16_bf16 v[32:47], v[88:91], v[168:171], v[32:47]
	ds_read_b64_tr_b16 v[168:169], v204 offset:0x1400
	ds_read_b64_tr_b16 v[170:171], v204 offset:0x1c00
	s_waitcnt lgkmcnt(6)
	v_mfma_f32_32x32x16_bf16 v[32:47], v[84:87], v[190:193], v[32:47]
	ds_read_b64_tr_b16 v[190:191], v204 offset:0x2400
	ds_read_b64_tr_b16 v[192:193], v204 offset:0x2c00
	ds_read_b64_tr_b16 v[194:195], v204 offset:0x3400
	ds_read_b64_tr_b16 v[196:197], v204 offset:0x3c00
	s_waitcnt lgkmcnt(8)
	v_mfma_f32_32x32x16_bf16 v[32:47], v[80:83], v[200:203], v[32:47]
	s_waitcnt lgkmcnt(6)
	v_mfma_f32_32x32x16_bf16 v[16:31], v[92:95], v[164:167], v[16:31]
	ds_read_b64_tr_b16 v[164:165], v204 offset:0x600
	ds_read_b64_tr_b16 v[166:167], v204 offset:0xe00
	s_waitcnt lgkmcnt(6)
	v_mfma_f32_32x32x16_bf16 v[16:31], v[88:91], v[168:171], v[16:31]
	ds_read_b64_tr_b16 v[168:169], v204 offset:0x1600
	ds_read_b64_tr_b16 v[170:171], v204 offset:0x1e00
	s_waitcnt lgkmcnt(6)
	v_mfma_f32_32x32x16_bf16 v[16:31], v[84:87], v[190:193], v[16:31]
	ds_read_b64_tr_b16 v[190:191], v204 offset:0x2600
	ds_read_b64_tr_b16 v[192:193], v204 offset:0x2e00
	ds_read_b64_tr_b16 v[200:201], v204 offset:0x3600
	ds_read_b64_tr_b16 v[202:203], v204 offset:0x3e00
	s_waitcnt lgkmcnt(8)
	v_mfma_f32_32x32x16_bf16 v[16:31], v[80:83], v[194:197], v[16:31]
	s_waitcnt lgkmcnt(6)
	v_mfma_f32_32x32x16_bf16 v[0:15], v[92:95], v[164:167], v[0:15]
	s_mov_b64 s[42:43], -1
	s_and_b64 vcc, exec, s[40:41]
	s_waitcnt lgkmcnt(4)
	v_mfma_f32_32x32x16_bf16 v[0:15], v[88:91], v[168:171], v[0:15]
	s_waitcnt lgkmcnt(2)
	v_mfma_f32_32x32x16_bf16 v[0:15], v[84:87], v[190:193], v[0:15]
	s_waitcnt lgkmcnt(0)
	v_mfma_f32_32x32x16_bf16 v[0:15], v[80:83], v[200:203], v[0:15]
	s_cbranch_vccz .LBB0_465
	s_waitcnt vmcnt(0)
	s_barrier
	s_mov_b64 s[42:43], 0
.LBB0_465:
	s_andn2_b64 vcc, exec, s[42:43]
	s_cbranch_vccnz .LBB0_460
	s_waitcnt vmcnt(4)
	s_barrier
	s_branch .LBB0_460

; __device__ __forceinline__ void finishSM(f32x16& p0, f32x16& p1, float alpha, float& l_reg, bf16x8& pa0, bf16x8& pa1, bf16x8& pa2, bf16x8& pa3) {
;   for (int r = 0; r < 16; ++r) p1[r] = __builtin_amdgcn_exp2f(p1[r]);
;   float ps = 0; for (int r = 0; r < 16; ++r) ps += p0[r]; for (int r = 0; r < 16; ++r) ps += p1[r];
;   asm volatile("" : "+v"(ps));
;   l_reg = l_reg * alpha + ps;
;     ...
;   PK4(p0, 0, pa0); PK4(p0, 8, pa1); PK4(p1, 0, pa2); PK4(p1, 8, pa3);
;     ...
; }
; __device__ __forceinline__ void qkt(f32x16& p0, f32x16& p1, const bf16* Ks, const bf16x8* qr, int r32, int hi) {
;   p0 = f32x16{}; p1 = f32x16{};
;   for (int d0 = 0; d0 < 8; ++d0) { int cb = (d0 * 16 + hi * 8) * 2;
;     bf16x8 b0 = *reinterpret_cast<const bf16x8*>((const char*)Ks + KSWZ(r32, cb));
;     bf16x8 b1 = *reinterpret_cast<const bf16x8*>((const char*)Ks + KSWZ(32 + r32, cb));
;     p0 = __builtin_amdgcn_mfma_f32_32x32x16_bf16(b0, qr[d0], p0, 0, 0, 0);
;     p1 = __builtin_amdgcn_mfma_f32_32x32x16_bf16(b1, qr[d0], p1, 0, 0, 0); }
; }
; __device__ __forceinline__ int v_st(int k, int c) { const int kk = k;
;   return ((kk >> 3) * 4 + (c >> 5)) * 512 + ((kk & 7) * 32 + (c & 31)) * 2; }
; __device__ __forceinline__ int v_rd_base(int lane) { return ((lane & 3) << 3) | (((lane >> 2) & 3) << 6) | (((lane >> 4) & 1) << 5) | (((lane >> 5) & 1) << 8); }
; template <int OFF> __device__ __forceinline__ s16x4 tr_read(int vb) {
;   s16x4 r; asm volatile("ds_read_b64_tr_b16 %0, %1 offset:%2" : "=&v"(r) : "v"(vb), "i"(OFF) : "memory"); return r;
; }
; template <int D0> __device__ __forceinline__ void pv_one(f32x16& od, int vb, bf16x8 pa0, bf16x8 pa1, bf16x8 pa2, bf16x8 pa3) {
;   const s16x4 l0 = tr_read<v_rd_off(D0, 0, 0)>(vb), h0 = tr_read<v_rd_off(D0, 0, 1)>(vb), l1 = tr_read<v_rd_off(D0, 1, 0)>(vb), h1 = tr_read<v_rd_off(D0, 1, 1)>(vb);
;   const s16x4 l2 = tr_read<v_rd_off(D0, 2, 0)>(vb), h2 = tr_read<v_rd_off(D0, 2, 1)>(vb), l3 = tr_read<v_rd_off(D0, 3, 0)>(vb), h3 = tr_read<v_rd_off(D0, 3, 1)>(vb);
;   asm volatile("s_waitcnt lgkmcnt(0)" ::: "memory"); SBAR();
;     ...
;   od = __builtin_amdgcn_mfma_f32_32x32x16_bf16(pa0, PK(l0, h0), od, 0, 0, 0);
;   od = __builtin_amdgcn_mfma_f32_32x32x16_bf16(pa1, PK(l1, h1), od, 0, 0, 0);
;   od = __builtin_amdgcn_mfma_f32_32x32x16_bf16(pa2, PK(l2, h2), od, 0, 0, 0);
;   od = __builtin_amdgcn_mfma_f32_32x32x16_bf16(pa3, PK(l3, h3), od, 0, 0, 0);
;     ...
; }
.LBB0_1365:
	s_mov_b32 s40, s33
	s_addk_i32 s33, 0xc000
	s_and_b32 s42, s33, 0xc000
	s_add_i32 s33, s56, s42
	v_add_u32_e32 v84, s33, v178
	ds_read_b128 v[80:83], v84
	ds_read_b128 v[84:87], v84 offset:8192
	v_add_u32_e32 v202, s33, v179
	ds_read_b128 v[198:201], v202
	ds_read_b128 v[202:205], v202 offset:8192
	v_add_u32_e32 v206, s33, v181
	s_waitcnt lgkmcnt(3)
	v_mfma_f32_32x32x16_bf16 v[96:111], v[80:83], v[136:139], 0
	v_add_u32_e32 v214, s33, v182
	v_exp_f32_e32 v238, v64
	v_add_f32_e32 v64, 0, v196
	v_add_f32_e32 v64, v197, v64
	v_add_u32_e32 v222, s33, v183
	v_add_f32_e32 v64, v193, v64
	v_add_f32_e32 v64, v195, v64
	s_waitcnt lgkmcnt(2)
	v_mfma_f32_32x32x16_bf16 v[80:95], v[84:87], v[136:139], 0
	v_add_f32_e32 v64, v191, v64
	v_add_f32_e32 v64, v194, v64
	v_add_f32_e32 v64, v190, v64
	v_add_f32_e32 v64, v192, v64
	v_add_f32_e32 v64, v169, v64
	v_add_f32_e32 v64, v171, v64
	v_add_u32_e32 v226, s33, v184
	s_waitcnt lgkmcnt(1)
	v_mfma_f32_32x32x16_bf16 v[96:111], v[198:201], v[140:143], v[96:111]
	v_add_f32_e32 v64, v167, v64
	v_add_f32_e32 v64, v170, v64
	v_add_f32_e32 v64, v165, v64
	v_add_f32_e32 v64, v168, v64
	v_add_f32_e32 v64, v164, v64
	v_add_f32_e32 v64, v166, v64
	v_exp_f32_e32 v239, v68
	s_waitcnt lgkmcnt(0)
	v_mfma_f32_32x32x16_bf16 v[80:95], v[202:205], v[140:143], v[80:95]
	v_add_u32_e32 v202, s33, v180
	ds_read_b128 v[198:201], v202
	ds_read_b128 v[202:205], v202 offset:8192
	v_add_f32_e32 v64, v238, v64
	v_exp_f32_e32 v240, v69
	v_add_u32_e32 v234, s33, v185
	v_exp_f32_e32 v241, v70
	v_exp_f32_e32 v242, v71
	s_waitcnt lgkmcnt(1)
	v_mfma_f32_32x32x16_bf16 v[96:111], v[198:201], v[132:135], v[96:111]
	ds_read_b128 v[198:201], v206
	ds_read_b128 v[206:209], v206 offset:8192
	ds_read_b128 v[210:213], v214
	ds_read_b128 v[214:217], v214 offset:8192
	ds_read_b128 v[218:221], v222
	ds_read_b128 v[222:225], v222 offset:8192
	v_exp_f32_e32 v243, v76
	v_exp_f32_e32 v244, v77
	v_exp_f32_e32 v245, v78
	v_exp_f32_e32 v79, v79
	s_waitcnt lgkmcnt(6)
	v_mfma_f32_32x32x16_bf16 v[80:95], v[202:205], v[132:135], v[80:95]
	ds_read_b128 v[202:205], v226
	ds_read_b128 v[226:229], v226 offset:8192
	ds_read_b128 v[230:233], v234
	ds_read_b128 v[234:237], v234 offset:8192
	s_waitcnt lgkmcnt(9)
	v_mfma_f32_32x32x16_bf16 v[96:111], v[198:201], v[128:131], v[96:111]
	v_exp_f32_e32 v199, v65
	v_exp_f32_e32 v200, v66
	v_exp_f32_e32 v201, v67
	v_add_f32_e32 v64, v199, v64
	v_add_f32_e32 v64, v200, v64
	v_add_f32_e32 v64, v201, v64
	s_waitcnt lgkmcnt(8)
	v_mfma_f32_32x32x16_bf16 v[80:95], v[206:209], v[128:131], v[80:95]
	v_exp_f32_e32 v206, v72
	v_add_f32_e32 v64, v239, v64
	v_exp_f32_e32 v207, v73
	v_add_f32_e32 v64, v240, v64
	v_exp_f32_e32 v208, v74
	v_add_f32_e32 v64, v241, v64
	v_exp_f32_e32 v209, v75
	s_waitcnt lgkmcnt(7)
	v_mfma_f32_32x32x16_bf16 v[96:111], v[210:213], v[124:127], v[96:111]
	v_add_f32_e32 v64, v242, v64
	v_add_f32_e32 v64, v206, v64
	v_add_f32_e32 v64, v207, v64
	v_add_f32_e32 v64, v208, v64
	v_add_f32_e32 v64, v209, v64
	v_add_f32_e32 v64, v243, v64
	v_add_f32_e32 v64, v244, v64
	s_waitcnt lgkmcnt(6)
	v_mfma_f32_32x32x16_bf16 v[80:95], v[214:217], v[124:127], v[80:95]
	v_add_f32_e32 v64, v245, v64
	v_add_f32_e32 v198, v79, v64
	v_cvt_pk_bf16_f32 v64, v196, v197
	v_cvt_pk_bf16_f32 v65, v193, v195
	v_cvt_pk_bf16_f32 v66, v191, v194
	v_cvt_pk_bf16_f32 v67, v190, v192
	s_waitcnt lgkmcnt(5)
	v_mfma_f32_32x32x16_bf16 v[96:111], v[218:221], v[120:123], v[96:111]
	v_cvt_pk_bf16_f32 v68, v169, v171
	v_cvt_pk_bf16_f32 v69, v167, v170
	v_cvt_pk_bf16_f32 v70, v165, v168
	v_cvt_pk_bf16_f32 v71, v164, v166
	v_cvt_pk_bf16_f32 v72, v238, v199
	v_cvt_pk_bf16_f32 v73, v200, v201
	v_cvt_pk_bf16_f32 v74, v239, v240
	s_waitcnt lgkmcnt(4)
	v_mfma_f32_32x32x16_bf16 v[80:95], v[222:225], v[120:123], v[80:95]
	v_cvt_pk_bf16_f32 v75, v241, v242
	v_cvt_pk_bf16_f32 v76, v206, v207
	v_cvt_pk_bf16_f32 v77, v208, v209
	v_cvt_pk_bf16_f32 v78, v243, v244
	v_cvt_pk_bf16_f32 v79, v245, v79
	s_waitcnt lgkmcnt(3)
	v_mfma_f32_32x32x16_bf16 v[96:111], v[202:205], v[116:119], v[96:111]
	s_waitcnt lgkmcnt(2)
	v_mfma_f32_32x32x16_bf16 v[80:95], v[226:229], v[116:119], v[80:95]
	s_waitcnt lgkmcnt(1)
	v_mfma_f32_32x32x16_bf16 v[96:111], v[230:233], v[112:115], v[96:111]
	s_waitcnt lgkmcnt(0)
	v_mfma_f32_32x32x16_bf16 v[80:95], v[234:237], v[112:115], v[80:95]
	s_add_i32 s33, s40, 0x4000
	s_and_b32 s33, s33, 0xc000
	v_lshl_add_u64 v[164:165], s[38:39], 0, v[156:157]
	s_add_i32 s41, s66, s33
	v_lshl_add_u64 v[166:167], v[164:165], 0, s[22:23]
	s_mov_b32 m0, s41
	s_add_i32 s33, s67, s33
	global_load_lds_dwordx4 v[166:167], off
	v_lshl_add_u64 v[166:167], s[38:39], 0, v[158:159]
	v_lshl_add_u64 v[168:169], v[166:167], 0, s[22:23]
	s_add_i32 m0, s41, 0x2000
	s_nop 0
	global_load_lds_dwordx4 v[168:169], off
	v_lshl_add_u64 v[168:169], s[38:39], 0, v[162:163]
	v_lshl_add_u64 v[170:171], v[168:169], 0, s[24:25]
	s_mov_b32 m0, s33
	s_nop 0
	global_load_lds_dwordx4 v[170:171], off
	v_lshl_add_u64 v[170:171], s[38:39], 0, v[160:161]
	v_lshl_add_u64 v[190:191], v[170:171], 0, s[24:25]
	s_add_i32 m0, s33, 0x2000
	s_nop 0
	global_load_lds_dwordx4 v[190:191], off
	s_add_i32 s33, s40, 0x8000
	s_and_b32 s43, s33, 0xc000
	v_add_u32_e32 v199, s43, v176
	ds_read_b64_tr_b16 v[190:191], v199 offset:0
	ds_read_b64_tr_b16 v[192:193], v199 offset:0x800
	ds_read_b64_tr_b16 v[194:195], v199 offset:0x1000
	ds_read_b64_tr_b16 v[196:197], v199 offset:0x1800
	ds_read_b64_tr_b16 v[200:201], v199 offset:0x2000
	ds_read_b64_tr_b16 v[202:203], v199 offset:0x2800
	ds_read_b64_tr_b16 v[204:205], v199 offset:0x3000
	ds_read_b64_tr_b16 v[206:207], v199 offset:0x3800
	s_nop 0
	s_waitcnt lgkmcnt(6)
; #define SBAR() __builtin_amdgcn_sched_barrier(0)
; #define PUBLISH(n) do { asm volatile("s_waitcnt vmcnt(" #n ")" ::: "memory"); asm volatile("s_waitcnt lgkmcnt(0)" ::: "memory"); __builtin_amdgcn_s_barrier(); SBAR(); } while (0)
; template <int D0> __device__ __forceinline__ void pv_one(f32x16& od, int vb, bf16x8 pa0, bf16x8 pa1, bf16x8 pa2, bf16x8 pa3) {
;   const s16x4 l0 = tr_read<v_rd_off(D0, 0, 0)>(vb), h0 = tr_read<v_rd_off(D0, 0, 1)>(vb), l1 = tr_read<v_rd_off(D0, 1, 0)>(vb), h1 = tr_read<v_rd_off(D0, 1, 1)>(vb);
;   const s16x4 l2 = tr_read<v_rd_off(D0, 2, 0)>(vb), h2 = tr_read<v_rd_off(D0, 2, 1)>(vb), l3 = tr_read<v_rd_off(D0, 3, 0)>(vb), h3 = tr_read<v_rd_off(D0, 3, 1)>(vb);
;   asm volatile("s_waitcnt lgkmcnt(0)" ::: "memory"); SBAR();
;     ...
;   od = __builtin_amdgcn_mfma_f32_32x32x16_bf16(pa0, PK(l0, h0), od, 0, 0, 0);
;   od = __builtin_amdgcn_mfma_f32_32x32x16_bf16(pa1, PK(l1, h1), od, 0, 0, 0);
;   od = __builtin_amdgcn_mfma_f32_32x32x16_bf16(pa2, PK(l2, h2), od, 0, 0, 0);
;   od = __builtin_amdgcn_mfma_f32_32x32x16_bf16(pa3, PK(l3, h3), od, 0, 0, 0);
;     ...
; }
; __device__ __forceinline__ void pv_d0(f32x16* o, int vb, bf16x8 pa0, bf16x8 pa1, bf16x8 pa2, bf16x8 pa3) {
;   pv_one<0>(o[0], vb, pa0, pa1, pa2, pa3); pv_one<1>(o[1], vb, pa0, pa1, pa2, pa3); pv_one<2>(o[2], vb, pa0, pa1, pa2, pa3); pv_one<3>(o[3], vb, pa0, pa1, pa2, pa3);
; }
; template <typename TQ> ...
;     ...
;     PUBLISH(4);
	v_mfma_f32_32x32x16_bf16 v[48:63], v[64:67], v[190:193], v[48:63]
	ds_read_b64_tr_b16 v[190:191], v199 offset:0x200
	ds_read_b64_tr_b16 v[192:193], v199 offset:0xa00
	s_waitcnt lgkmcnt(6)
	v_mfma_f32_32x32x16_bf16 v[48:63], v[68:71], v[194:197], v[48:63]
	ds_read_b64_tr_b16 v[194:195], v199 offset:0x1200
	ds_read_b64_tr_b16 v[196:197], v199 offset:0x1a00
	s_waitcnt lgkmcnt(6)
	v_mfma_f32_32x32x16_bf16 v[48:63], v[72:75], v[200:203], v[48:63]
	ds_read_b64_tr_b16 v[200:201], v199 offset:0x2200
	ds_read_b64_tr_b16 v[202:203], v199 offset:0x2a00
	ds_read_b64_tr_b16 v[208:209], v199 offset:0x3200
	ds_read_b64_tr_b16 v[210:211], v199 offset:0x3a00
	s_waitcnt lgkmcnt(8)
	v_mfma_f32_32x32x16_bf16 v[48:63], v[76:79], v[204:207], v[48:63]
	s_waitcnt lgkmcnt(6)
	v_mfma_f32_32x32x16_bf16 v[32:47], v[64:67], v[190:193], v[32:47]
	ds_read_b64_tr_b16 v[190:191], v199 offset:0x400
	ds_read_b64_tr_b16 v[192:193], v199 offset:0xc00
	s_waitcnt lgkmcnt(6)
	v_mfma_f32_32x32x16_bf16 v[32:47], v[68:71], v[194:197], v[32:47]
	ds_read_b64_tr_b16 v[194:195], v199 offset:0x1400
	ds_read_b64_tr_b16 v[196:197], v199 offset:0x1c00
	s_waitcnt lgkmcnt(6)
	v_mfma_f32_32x32x16_bf16 v[32:47], v[72:75], v[200:203], v[32:47]
	ds_read_b64_tr_b16 v[200:201], v199 offset:0x2400
	ds_read_b64_tr_b16 v[202:203], v199 offset:0x2c00
	ds_read_b64_tr_b16 v[204:205], v199 offset:0x3400
	ds_read_b64_tr_b16 v[206:207], v199 offset:0x3c00
	s_waitcnt lgkmcnt(8)
	v_mfma_f32_32x32x16_bf16 v[32:47], v[76:79], v[208:211], v[32:47]
	s_waitcnt lgkmcnt(6)
	v_mfma_f32_32x32x16_bf16 v[16:31], v[64:67], v[190:193], v[16:31]
	ds_read_b64_tr_b16 v[190:191], v199 offset:0x600
	ds_read_b64_tr_b16 v[192:193], v199 offset:0xe00
	s_waitcnt lgkmcnt(6)
	v_mfma_f32_32x32x16_bf16 v[16:31], v[68:71], v[194:197], v[16:31]
	ds_read_b64_tr_b16 v[194:195], v199 offset:0x1600
	ds_read_b64_tr_b16 v[196:197], v199 offset:0x1e00
	s_waitcnt lgkmcnt(6)
	v_mfma_f32_32x32x16_bf16 v[16:31], v[72:75], v[200:203], v[16:31]
	ds_read_b64_tr_b16 v[200:201], v199 offset:0x2600
	ds_read_b64_tr_b16 v[202:203], v199 offset:0x2e00
	ds_read_b64_tr_b16 v[208:209], v199 offset:0x3600
	ds_read_b64_tr_b16 v[210:211], v199 offset:0x3e00
	s_waitcnt lgkmcnt(8)
	v_mfma_f32_32x32x16_bf16 v[16:31], v[76:79], v[204:207], v[16:31]
	s_waitcnt lgkmcnt(6)
	v_mfma_f32_32x32x16_bf16 v[0:15], v[64:67], v[190:193], v[0:15]
	s_waitcnt vmcnt(4)
	v_exp_f32_e32 v232, v96
	v_exp_f32_e32 v233, v97
	v_exp_f32_e32 v234, v98
	v_exp_f32_e32 v235, v99
	v_exp_f32_e32 v236, v100
	s_waitcnt lgkmcnt(4)
	v_mfma_f32_32x32x16_bf16 v[0:15], v[68:71], v[194:197], v[0:15]
	v_exp_f32_e32 v237, v101
	v_exp_f32_e32 v238, v102
	v_exp_f32_e32 v239, v103
	v_exp_f32_e32 v240, v104
	v_exp_f32_e32 v241, v105
	v_exp_f32_e32 v242, v106
	v_exp_f32_e32 v243, v107
	s_waitcnt lgkmcnt(2)
	v_mfma_f32_32x32x16_bf16 v[0:15], v[72:75], v[200:203], v[0:15]
	v_exp_f32_e32 v244, v108
	v_exp_f32_e32 v245, v109
	v_exp_f32_e32 v246, v110
	v_exp_f32_e32 v247, v111
	s_waitcnt lgkmcnt(0)
	s_barrier
; #define SBAR() __builtin_amdgcn_sched_barrier(0)
; #define PK4(P, BASE, OUT) do { u32x4 w = {cvtpk(P[BASE + 0], P[BASE + 1]), cvtpk(P[BASE + 2], P[BASE + 3]), cvtpk(P[BASE + 4], P[BASE + 5]), cvtpk(P[BASE + 6], P[BASE + 7])}; \
;     OUT = *reinterpret_cast<bf16x8*>(&w); } while (0)
; __device__ __forceinline__ void finishSM(f32x16& p0, f32x16& p1, float alpha, float& l_reg, bf16x8& pa0, bf16x8& pa1, bf16x8& pa2, bf16x8& pa3) {
;   for (int r = 0; r < 16; ++r) p1[r] = __builtin_amdgcn_exp2f(p1[r]);
;   float ps = 0; for (int r = 0; r < 16; ++r) ps += p0[r]; for (int r = 0; r < 16; ++r) ps += p1[r];
;   asm volatile("" : "+v"(ps));
;   l_reg = l_reg * alpha + ps;
;     ...
;   PK4(p0, 0, pa0); PK4(p0, 8, pa1); PK4(p1, 0, pa2); PK4(p1, 8, pa3);
;     ...
; }
; __device__ __forceinline__ void qkt(f32x16& p0, f32x16& p1, const bf16* Ks, const bf16x8* qr, int r32, int hi) {
;   p0 = f32x16{}; p1 = f32x16{};
;   for (int d0 = 0; d0 < 8; ++d0) { int cb = (d0 * 16 + hi * 8) * 2;
;     bf16x8 b0 = *reinterpret_cast<const bf16x8*>((const char*)Ks + KSWZ(r32, cb));
;     bf16x8 b1 = *reinterpret_cast<const bf16x8*>((const char*)Ks + KSWZ(32 + r32, cb));
;     p0 = __builtin_amdgcn_mfma_f32_32x32x16_bf16(b0, qr[d0], p0, 0, 0, 0);
;     p1 = __builtin_amdgcn_mfma_f32_32x32x16_bf16(b1, qr[d0], p1, 0, 0, 0); }
; }
; template <typename TQ> ...
;     ...
;     SBAR(); qkt(pA0, pA1, (const bf16*)(K_lds + ((j + 1) & 3) * (int)SHM_K), qr, r32, hi);
;     finishSM(pB0, pB1, alB, l_reg, pa0, pa1, pa2, pa3); SBAR();
;     if (j + 3 < NT) { DMA_TILE(j + 3, (j + 3) & 3); } SBAR();
	v_mfma_f32_32x32x16_bf16 v[0:15], v[76:79], v[208:211], v[0:15]
	s_and_b32 s40, s40, 0xc000
	s_add_i32 s40, s56, s40
	v_add_u32_e32 v68, s40, v178
	ds_read_b128 v[64:67], v68
	ds_read_b128 v[68:71], v68 offset:8192
	v_add_u32_e32 v194, s40, v179
	ds_read_b128 v[190:193], v194
	ds_read_b128 v[194:197], v194 offset:8192
	v_add_u32_e32 v199, s40, v181
	s_waitcnt lgkmcnt(3)
	v_mfma_f32_32x32x16_bf16 v[96:111], v[64:67], v[136:139], 0
	v_exp_f32_e32 v80, v80
	v_exp_f32_e32 v81, v81
	v_exp_f32_e32 v82, v82
	v_exp_f32_e32 v83, v83
	v_exp_f32_e32 v87, v87
	v_exp_f32_e32 v248, v93
	v_exp_f32_e32 v249, v94
	s_waitcnt lgkmcnt(2)
	v_mfma_f32_32x32x16_bf16 v[64:79], v[68:71], v[136:139], 0
	s_waitcnt lgkmcnt(1)
	v_mfma_f32_32x32x16_bf16 v[96:111], v[190:193], v[140:143], v[96:111]
	s_waitcnt lgkmcnt(0)
	v_mfma_f32_32x32x16_bf16 v[64:79], v[194:197], v[140:143], v[64:79]
	v_add_u32_e32 v194, s40, v180
	ds_read_b128 v[190:193], v194
	ds_read_b128 v[194:197], v194 offset:8192
	s_waitcnt lgkmcnt(1)
	v_mfma_f32_32x32x16_bf16 v[96:111], v[190:193], v[132:135], v[96:111]
	ds_read_b128 v[190:193], v199
	ds_read_b128 v[200:203], v199 offset:8192
	v_add_u32_e32 v199, s40, v182
	ds_read_b128 v[204:207], v199
	ds_read_b128 v[208:211], v199 offset:8192
	v_add_u32_e32 v199, s40, v183
	ds_read_b128 v[212:215], v199
	ds_read_b128 v[216:219], v199 offset:8192
	v_add_u32_e32 v199, s40, v184
	s_waitcnt lgkmcnt(6)
	v_mfma_f32_32x32x16_bf16 v[64:79], v[194:197], v[132:135], v[64:79]
	ds_read_b128 v[194:197], v199
	ds_read_b128 v[220:223], v199 offset:8192
	v_add_u32_e32 v199, s40, v185
	ds_read_b128 v[224:227], v199
	ds_read_b128 v[228:231], v199 offset:8192
	s_waitcnt lgkmcnt(9)
	v_mfma_f32_32x32x16_bf16 v[96:111], v[190:193], v[128:131], v[96:111]
	v_exp_f32_e32 v190, v84
	v_add_f32_e32 v84, 0, v232
	v_add_f32_e32 v84, v233, v84
	v_add_f32_e32 v84, v234, v84
	v_add_f32_e32 v84, v235, v84
	v_add_f32_e32 v84, v236, v84
	v_add_f32_e32 v84, v237, v84
	s_waitcnt lgkmcnt(8)
	v_mfma_f32_32x32x16_bf16 v[64:79], v[200:203], v[128:131], v[64:79]
	v_add_f32_e32 v84, v238, v84
	v_add_f32_e32 v84, v239, v84
	v_add_f32_e32 v84, v240, v84
	v_add_f32_e32 v84, v241, v84
	v_add_f32_e32 v84, v242, v84
	v_add_f32_e32 v84, v243, v84
	v_add_f32_e32 v84, v244, v84
	s_waitcnt lgkmcnt(7)
	v_mfma_f32_32x32x16_bf16 v[96:111], v[204:207], v[124:127], v[96:111]
	v_add_f32_e32 v84, v245, v84
	v_add_f32_e32 v84, v246, v84
	v_add_f32_e32 v84, v247, v84
	v_add_f32_e32 v84, v80, v84
	v_exp_f32_e32 v191, v85
	v_add_f32_e32 v84, v81, v84
	v_exp_f32_e32 v192, v86
	s_waitcnt lgkmcnt(6)
	v_mfma_f32_32x32x16_bf16 v[64:79], v[208:211], v[124:127], v[64:79]
	v_add_f32_e32 v84, v82, v84
	v_add_f32_e32 v84, v83, v84
	v_exp_f32_e32 v193, v88
	v_add_f32_e32 v84, v190, v84
	v_exp_f32_e32 v200, v89
	v_add_f32_e32 v84, v191, v84
	v_exp_f32_e32 v201, v90
	s_waitcnt lgkmcnt(5)
	v_mfma_f32_32x32x16_bf16 v[96:111], v[212:215], v[120:123], v[96:111]
	v_add_f32_e32 v84, v192, v84
	v_exp_f32_e32 v202, v91
	v_add_f32_e32 v84, v87, v84
	v_exp_f32_e32 v203, v92
	v_add_f32_e32 v84, v193, v84
	v_add_f32_e32 v84, v200, v84
	v_add_f32_e32 v84, v201, v84
	s_waitcnt lgkmcnt(4)
	v_mfma_f32_32x32x16_bf16 v[64:79], v[216:219], v[120:123], v[64:79]
	v_exp_f32_e32 v204, v95
	v_add_f32_e32 v84, v202, v84
	v_add_f32_e32 v84, v203, v84
	v_add_f32_e32 v84, v248, v84
	v_add_f32_e32 v84, v249, v84
	v_add_f32_e32 v199, v204, v84
	s_waitcnt lgkmcnt(3)
	v_mfma_f32_32x32x16_bf16 v[96:111], v[194:197], v[116:119], v[96:111]
	v_cvt_pk_bf16_f32 v92, v232, v233
	v_cvt_pk_bf16_f32 v93, v234, v235
	v_cvt_pk_bf16_f32 v94, v236, v237
	v_cvt_pk_bf16_f32 v95, v238, v239
	v_cvt_pk_bf16_f32 v88, v240, v241
	v_cvt_pk_bf16_f32 v89, v242, v243
	v_cvt_pk_bf16_f32 v90, v244, v245
	s_waitcnt lgkmcnt(2)
	v_mfma_f32_32x32x16_bf16 v[64:79], v[220:223], v[116:119], v[64:79]
	v_cvt_pk_bf16_f32 v91, v246, v247
	v_cvt_pk_bf16_f32 v84, v80, v81
	v_cvt_pk_bf16_f32 v85, v82, v83
	v_cvt_pk_bf16_f32 v86, v190, v191
	v_cvt_pk_bf16_f32 v87, v192, v87
	v_cvt_pk_bf16_f32 v80, v193, v200
	v_cvt_pk_bf16_f32 v81, v201, v202
	s_waitcnt lgkmcnt(1)
	v_mfma_f32_32x32x16_bf16 v[96:111], v[224:227], v[112:115], v[96:111]
	v_cvt_pk_bf16_f32 v82, v203, v248
	v_cvt_pk_bf16_f32 v83, v249, v204
	s_waitcnt lgkmcnt(0)
	v_mfma_f32_32x32x16_bf16 v[64:79], v[228:231], v[112:115], v[64:79]
	s_cmp_ge_u32 s72, s37
	s_cselect_b64 s[40:41], -1, 0
	s_and_b64 vcc, exec, s[40:41]
	s_cbranch_vccnz .LBB0_1367
	s_add_i32 s73, s66, s43
	v_lshl_add_u64 v[164:165], v[164:165], 0, s[26:27]
	s_mov_b32 m0, s73
	s_add_i32 s43, s67, s43
	global_load_lds_dwordx4 v[164:165], off
	v_lshl_add_u64 v[164:165], v[166:167], 0, s[26:27]
	s_add_i32 m0, s73, 0x2000
	s_nop 0
	global_load_lds_dwordx4 v[164:165], off
	v_lshl_add_u64 v[164:165], v[168:169], 0, s[28:29]
	s_mov_b32 m0, s43
	s_nop 0
	global_load_lds_dwordx4 v[164:165], off
	v_lshl_add_u64 v[164:165], v[170:171], 0, s[28:29]
	s_add_i32 m0, s43, 0x2000
	s_nop 0
	global_load_lds_dwordx4 v[164:165], off
